# prompt attention restructured: unit = 256 q rows x one map x both value halves, wave = 32 q rows x all 64 keys of a tile (K and V staged once per 256 rows, no cross-wave merge); K tile image row-conti
# speedup vs baseline: 1.1210x; 1.0385x over previous
; template<int THRL,bool PART> __device__ __forceinline__ int attn_unit(const bf16*Qb,const bf16*__restrict__ Kh,const bf16*__restrict__ Vh,bf16*Ob,const int NT,const int vlim_in,char*shm,const int s0,const bool primed,const bf16*nKh,const bf16*nVh,bf16*fuseM,const float lam){
;   int tid=threadIdx.x; asm volatile("":"+v"(tid));
;   const int lane=tid&63,r32=lane&31,hi=lane>>5; const int wid=__builtin_amdgcn_readfirstlane(tid>>6);
;   const int vlim=(vlim_in<0)?(wid>>1):vlim_in;
;   const bool act=PART?(wid<2):true;
;   const bf16*Qw=Qb+(long)(wid*QBLK)*KP;
;   const unsigned lds0=(unsigned)(uintptr_t)shm;
;   float*wsf=(float*)(shm+LDS_WS)+wid*64;
;   const bf16*ksrc=Kh+(long)lane*KP+wid*8;
;   const bf16*vsrc=Vh+(long)(16*(wid&3)+(lane>>2))*KP+(wid>>2)*32+(lane&3)*8;
;   const unsigned kdst=lds0+LDS_K+wid*1024, vdst=lds0+LDS_V+wid*1024;
;     ...
;   const int vb0=(int)(lds0+LDS_V)+((lane>>4)&1)*32+(lane&3)*8+(4*hi+((lane&15)>>2))*64;
;   const int s1=(s0==(NSLOT-1)*SLOTB)?0:s0+SLOTB, s2=(s1==(NSLOT-1)*SLOTB)?0:s1+SLOTB;
;   const char*Kbase=shm+LDS_K+s0; bf16x8 kf[8];
;   const lds_cptr shm3=(lds_cptr)shm; const lds_cptr kp0=shm3+LDS_K+hi*1024+r32*16; const lds_cptr vp0=shm3+LDS_V+((lane>>4)&1)*32+(lane&3)*8+(4*hi+((lane&15)>>2))*64;
; __global__ void __launch_bounds__(NWAVES * 64, 2) mk_fwd(Args args) {
;     ...
;         for (int v = vcu; v < 256; v += G) {
;             const int bh = v >> 3, s = v & 7, b = bh >> 2, hd = bh & 3;
;             int ring0 = 0; bool primed = false;
;             for (int i = 0; i < 8; ++i) { const int qb = (i >> 2) ? 15 - s : s, j = (i >> 1) & 1, vh = i & 1;
;                 const bf16* Qp = Qb + (size_t)(b * 4096 + qb * 256) * 512 + (hd * 2 + j) * 64; const bf16* Kp = Kb + (size_t)(b * 4096) * 512 + (hd * 2 + j) * 64; const bf16* Vp = Vb + (size_t)(b * 4096) * 512 + (hd * 2 + vh) * 64;
;                 bf16* Op = ATTO + (size_t)(b * 4096 + qb * 256) * 1024 + ((hd * 2 + j) * 2 + vh) * 64;
;                 bf16* Mp = ((i & 3) == 3) ? H + (size_t)(b * 4096 + qb * 256) * 1024 + 512 + hd * 128 : nullptr;
.LBB0_925:
	s_cmpk_gt_i32 s92, 0xff
	s_waitcnt vmcnt(0) lgkmcnt(0)
	s_barrier
	s_cbranch_scc1 .LBB0_1021
	v_mov_b32_e32 v3, 0x1a0000
	global_load_dword v217, v3, s[66:67]
	v_and_b32_e32 v0, 63, v252
	v_and_b32_e32 v1, 31, v252
	v_bfe_u32 v2, v252, 5, 1
	v_lshrrev_b32_e32 v3, 6, v252
	s_nop 0
	v_readfirstlane_b32 s4, v3
	s_and_b32 s5, s4, 3
	s_lshr_b32 s6, s4, 2
	s_mov_b32 s48, 0x41000000
	v_bfe_u32 v219, v1, 1, 3
	v_lshlrev_b32_e32 v220, 7, v1
	v_or_b32_e32 v221, 0, v2
	v_xor_b32_e32 v221, v221, v219
	v_lshl_add_u32 v235, v221, 4, v220
	v_or_b32_e32 v221, 2, v2
	v_xor_b32_e32 v221, v221, v219
	v_lshl_add_u32 v236, v221, 4, v220
	v_or_b32_e32 v221, 4, v2
	v_xor_b32_e32 v221, v221, v219
	v_lshl_add_u32 v237, v221, 4, v220
	v_or_b32_e32 v221, 6, v2
	v_xor_b32_e32 v221, v221, v219
	v_lshl_add_u32 v238, v221, 4, v220
	v_bfe_u32 v218, v0, 4, 1
	v_lshlrev_b32_e32 v229, 5, v218
	v_and_b32_e32 v218, 3, v0
	v_lshl_add_u32 v229, v218, 3, v229
	v_bfe_u32 v218, v0, 2, 2
	v_lshl_add_u32 v218, v2, 2, v218
	v_lshl_add_u32 v229, v218, 6, v229
	s_lshl_b32 s34, s4, 10
	s_add_i32 s34, s34, 0x18000
	v_mov_b32_e32 v230, s34
	v_lshlrev_b32_e32 v240, 2, v1
	v_lshlrev_b32_e32 v241, 4, v2
	v_lshrrev_b32_e32 v218, 3, v0
	s_lshl_b32 s34, s4, 3
	v_add_u32_e32 v218, s34, v218
	v_bfe_u32 v219, v218, 1, 3
	v_and_b32_e32 v220, 7, v0
	v_xor_b32_e32 v219, v219, v220
	v_lshlrev_b32_e32 v231, 10, v218
	v_lshl_add_u32 v231, v219, 4, v231
	v_lshrrev_b32_e32 v218, 2, v0
	v_lshlrev_b32_e32 v232, 10, v218
	v_and_b32_e32 v218, 3, v0
	v_lshl_add_u32 v232, v218, 4, v232
	s_lshl_b32 s34, s5, 14
	s_lshl_b32 s35, s6, 6
	s_add_i32 s34, s34, s35
	v_add_u32_e32 v232, s34, v232
	v_add_u32_e32 v233, 0x80, v232
	v_lshlrev_b32_e32 v234, 10, v1
	v_lshl_add_u32 v234, v2, 4, v234
	v_lshlrev_b32_e32 v239, 4, v0
	s_lshl_b32 s34, s92, 3
	s_add_i32 s34, s34, s4
	s_lshl_b32 s34, s34, 14
	s_add_u32 s52, s66, s34
	s_addc_u32 s53, s67, 0
	s_add_u32 s52, s52, 0x6f00000
	s_addc_u32 s53, s53, 0
	s_waitcnt vmcnt(0)
	v_readfirstlane_b32 s7, v217
	s_mov_b32 s8, s92

;   #define DMA_K(t,slot) glds16(ksrc+(long)(t)*KVBLK*KP,(unsigned)__builtin_amdgcn_readfirstlane(kdst+(slot)))
;   #define DMA_V(t,slot) glds16(vsrc+(long)(t)*KVBLK*KP,(unsigned)__builtin_amdgcn_readfirstlane(vdst+(slot)))
; template<int THRL,bool PART> __device__ __forceinline__ int attn_unit(const bf16*Qb,const bf16*__restrict__ Kh,const bf16*__restrict__ Vh,bf16*Ob,const int NT,const int vlim_in,char*shm,const int s0,const bool primed,const bf16*nKh,const bf16*nVh,bf16*fuseM,const float lam){
;     ...
;   if(!primed){DMA_K(0,s0);DMA_V(0,s0);DMA_K(1,s1);}
;   bf16x8 qr[4];
;   #pragma unroll
;   for(int d0=0;d0<4;++d0)qr[d0]=*reinterpret_cast<const bf16x8*>(&Qw[(long)r32*KP+d0*16+hi*8]);
;   float zz_=0.f;asm volatile("":"+v"(zz_));
;   float mhat=zz_,l_reg=zz_;f32x16 o[2];
;   _Pragma("unroll") for(int r=0;r<16;++r){o[0][r]=zz_;o[1][r]=zz_;}
;   f32x16 negm;
;   _Pragma("unroll") for(int r=0;r<16;++r)negm[r]=zz_;
;   asm volatile("":"+v"(negm));
; __global__ void __launch_bounds__(NWAVES * 64, 2) mk_fwd(Args args) {
;     ...
;             for (int i = 0; i < 8; ++i) { const int qb = (i >> 2) ? 15 - s : s, j = (i >> 1) & 1, vh = i & 1;
;                 const bf16* Qp = Qb + (size_t)(b * 4096 + qb * 256) * 512 + (hd * 2 + j) * 64; const bf16* Kp = Kb + (size_t)(b * 4096) * 512 + (hd * 2 + j) * 64; const bf16* Vp = Vb + (size_t)(b * 4096) * 512 + (hd * 2 + vh) * 64;
;                 bf16* Op = ATTO + (size_t)(b * 4096 + qb * 256) * 1024 + ((hd * 2 + j) * 2 + vh) * 64;
;                 bf16* Mp = ((i & 3) == 3) ? H + (size_t)(b * 4096 + qb * 256) * 1024 + 512 + hd * 128 : nullptr;
;                 const bool more = i < 7; const int jn = ((i + 1) >> 1) & 1, vn = (i + 1) & 1;
;                 const bf16* nK = Kb + (size_t)(b * 4096) * 512 + (hd * 2 + jn) * 64; const bf16* nV = Vb + (size_t)(b * 4096) * 512 + (hd * 2 + vn) * 64;
;                 ring0 = attn_body::attn_unit<8, false>((const attn_body::bf16*)Qp, (const attn_body::bf16*)Kp, (const attn_body::bf16*)Vp, (attn_body::bf16*)Op, 4 * (qb + 1), -1, (char*)lds, ring0, primed,
.Lat_blk:
	s_sub_i32 s34, 15, s11
	s_cmp_eq_u32 s12, 0
	s_cselect_b32 s13, s11, s34
	s_lshl_b32 s15, s13, 2
	s_add_i32 s15, s15, 4
	s_lshr_b32 s34, s4, 1
	s_add_i32 s16, s15, s34
	s_sub_i32 s16, s16, 3
	s_mov_b32 s14, 0
.Lat_j:
	s_lshl_b32 s34, s10, 1
	s_add_i32 s34, s34, s14
	s_add_u32 s18, s66, 0xf300000
	s_addc_u32 s19, s67, 0
	s_lshl_b32 s36, s9, 22
	s_add_u32 s18, s18, s36
	s_addc_u32 s19, s19, 0
	s_lshl_b32 s36, s34, 7
	s_add_u32 s18, s18, s36
	s_addc_u32 s19, s19, 0
	s_add_u32 s20, s66, 0x12200000
	s_addc_u32 s21, s67, 0
	s_lshl_b32 s36, s9, 22
	s_add_u32 s20, s20, s36
	s_addc_u32 s21, s21, 0
	s_lshl_b32 s36, s10, 8
	s_add_u32 s20, s20, s36
	s_addc_u32 s21, s21, 0
	s_add_u32 s22, s66, 0xd100000
	s_addc_u32 s23, s67, 0
	s_lshl_b32 s36, s9, 22
	s_add_u32 s22, s22, s36
	s_addc_u32 s23, s23, 0
	s_lshl_b32 s36, s13, 18
	s_add_u32 s22, s22, s36
	s_addc_u32 s23, s23, 0
	s_lshl_b32 s36, s4, 15
	s_add_u32 s22, s22, s36
	s_addc_u32 s23, s23, 0
	s_lshl_b32 s36, s34, 7
	s_add_u32 s22, s22, s36
	s_addc_u32 s23, s23, 0
	s_mov_b32 s17, 0
	s_mov_b32 s24, 0
	global_load_dwordx4 v[4:7], v234, s[22:23]
	global_load_dwordx4 v[8:11], v234, s[22:23] offset:32
	global_load_dwordx4 v[12:15], v234, s[22:23] offset:64
	global_load_dwordx4 v[16:19], v234, s[22:23] offset:96
	s_mov_b32 s27, 0x0
	s_lshl_b32 s37, s4, 10
	s_add_i32 m0, s37, s27
	s_nop 0
	global_load_lds_dwordx4 v231, s[18:19]
	s_add_u32 s18, s18, 0x10000
	s_addc_u32 s19, s19, 0
	s_mov_b32 s27, 0x2000
	s_lshl_b32 s37, s4, 10
	s_add_i32 m0, s37, s27
	s_nop 0
	global_load_lds_dwordx4 v231, s[18:19]
	s_add_u32 s18, s18, 0x10000
	s_addc_u32 s19, s19, 0
	s_mov_b32 s27, 0x4000
	s_lshl_b32 s37, s4, 10
	s_add_i32 m0, s37, s27
	s_nop 0
	global_load_lds_dwordx4 v231, s[18:19]
	s_add_u32 s18, s18, 0x10000
	s_addc_u32 s19, s19, 0
	s_mov_b32 s27, 0x6000
	s_lshl_b32 s37, s4, 10
	s_add_i32 m0, s37, s27
	s_nop 0
	global_load_lds_dwordx4 v231, s[18:19]
	s_add_u32 s18, s18, 0x10000
	s_addc_u32 s19, s19, 0
	s_mov_b32 s29, 0x8000
	s_lshl_b32 s37, s4, 10
	s_add_i32 m0, s37, s29
	s_nop 0
	global_load_lds_dwordx4 v232, s[20:21]
	s_add_i32 m0, m0, 0x2000
	s_nop 0
	global_load_lds_dwordx4 v233, s[20:21]
	s_add_u32 s20, s20, 0x10000
	s_addc_u32 s21, s21, 0
	s_mov_b32 s29, 0xc000
	s_lshl_b32 s37, s4, 10
	s_add_i32 m0, s37, s29
	s_nop 0
	global_load_lds_dwordx4 v232, s[20:21]
	s_add_i32 m0, m0, 0x2000
	s_nop 0
	global_load_lds_dwordx4 v233, s[20:21]
	s_add_u32 s20, s20, 0x10000
	s_addc_u32 s21, s21, 0
	v_mov_b32_e32 v148, 0
	v_mov_b32_e32 v149, 0
	v_mov_b32_e32 v150, 0
	v_mov_b32_e32 v151, 0
	v_mov_b32_e32 v152, 0
	v_mov_b32_e32 v153, 0
	v_mov_b32_e32 v154, 0
	v_mov_b32_e32 v155, 0
	v_mov_b32_e32 v156, 0
	v_mov_b32_e32 v157, 0
	v_mov_b32_e32 v158, 0
	v_mov_b32_e32 v159, 0
	v_mov_b32_e32 v160, 0
	v_mov_b32_e32 v161, 0
	v_mov_b32_e32 v162, 0
	v_mov_b32_e32 v163, 0
	v_mov_b32_e32 v164, 0
	v_mov_b32_e32 v165, 0
	v_mov_b32_e32 v166, 0
	v_mov_b32_e32 v167, 0
	v_mov_b32_e32 v168, 0
	v_mov_b32_e32 v169, 0
	v_mov_b32_e32 v170, 0
	v_mov_b32_e32 v171, 0
	v_mov_b32_e32 v172, 0
	v_mov_b32_e32 v173, 0
	v_mov_b32_e32 v174, 0
	v_mov_b32_e32 v175, 0
	v_mov_b32_e32 v176, 0
	v_mov_b32_e32 v177, 0
	v_mov_b32_e32 v178, 0
	v_mov_b32_e32 v179, 0
	v_mov_b32_e32 v180, 0
	v_mov_b32_e32 v181, 0
	v_mov_b32_e32 v182, 0
	v_mov_b32_e32 v183, 0
	v_mov_b32_e32 v184, 0
	v_mov_b32_e32 v185, 0
	v_mov_b32_e32 v186, 0
	v_mov_b32_e32 v187, 0
	v_mov_b32_e32 v188, 0
	v_mov_b32_e32 v189, 0
	v_mov_b32_e32 v190, 0
	v_mov_b32_e32 v191, 0
	v_mov_b32_e32 v192, 0
	v_mov_b32_e32 v193, 0
	v_mov_b32_e32 v194, 0
	v_mov_b32_e32 v195, 0
	v_mov_b32_e32 v196, 0
	v_mov_b32_e32 v197, 0
	v_mov_b32_e32 v198, 0
	v_mov_b32_e32 v199, 0
	v_mov_b32_e32 v200, 0
	v_mov_b32_e32 v201, 0
	v_mov_b32_e32 v202, 0
	v_mov_b32_e32 v203, 0
	v_mov_b32_e32 v204, 0
	v_mov_b32_e32 v205, 0
	v_mov_b32_e32 v206, 0
	v_mov_b32_e32 v207, 0
	v_mov_b32_e32 v208, 0
	v_mov_b32_e32 v209, 0
	v_mov_b32_e32 v210, 0
	v_mov_b32_e32 v211, 0
	v_mov_b32_e32 v84, 0
	v_mov_b32_e32 v85, 0
	v_mov_b32_e32 v86, 0
	v_mov_b32_e32 v87, 0
	v_mov_b32_e32 v88, 0
	v_mov_b32_e32 v89, 0
	v_mov_b32_e32 v90, 0
	v_mov_b32_e32 v91, 0
	v_mov_b32_e32 v92, 0
	v_mov_b32_e32 v93, 0
	v_mov_b32_e32 v94, 0
	v_mov_b32_e32 v95, 0
	v_mov_b32_e32 v96, 0
	v_mov_b32_e32 v97, 0
	v_mov_b32_e32 v98, 0
	v_mov_b32_e32 v99, 0
	v_mov_b32_e32 v212, 0
	v_mov_b32_e32 v213, 0
	s_waitcnt vmcnt(0)
	s_barrier
	ds_read_b128 v[20:23], v235
	ds_read_b128 v[24:27], v236
	ds_read_b128 v[28:31], v237
	ds_read_b128 v[32:35], v238
	ds_read_b128 v[36:39], v235 offset:4096
	ds_read_b128 v[40:43], v236 offset:4096
	ds_read_b128 v[44:47], v237 offset:4096
	ds_read_b128 v[48:51], v238 offset:4096
.Lat_t1:
	s_add_i32 s26, s24, 1
	s_and_b32 s26, s26, 3
	s_lshl_b32 s26, s26, 13
	s_lshl_b32 s27, s24, 13
	s_add_i32 s28, s24, 3
	s_and_b32 s28, s28, 3
	s_lshl_b32 s28, s28, 14
	s_add_i32 s28, s28, 0x8000
	s_add_i32 s29, s24, 2
	s_and_b32 s29, s29, 3
	s_lshl_b32 s29, s29, 14
	s_add_i32 s29, s29, 0x8000
	s_cmp_lt_u32 s17, s16
	s_cbranch_scc0 .Lat_last4
	s_cmp_eq_u32 s17, 0
	s_cbranch_scc1 .Lat_first3
	v_add_u32_e32 v218, s28, v229
	ds_read_b64_tr_b16 v[116:117], v218 offset:0
	ds_read_b64_tr_b16 v[118:119], v218 offset:512
	v_mfma_f32_32x32x16_bf16 v[52:67], v[20:23], v[4:7], v[84:99]
	ds_read_b64_tr_b16 v[120:121], v218 offset:4096
	ds_read_b64_tr_b16 v[122:123], v218 offset:4608
	v_mfma_f32_32x32x16_bf16 v[52:67], v[24:27], v[8:11], v[52:67]
	ds_read_b64_tr_b16 v[124:125], v218 offset:8192
	ds_read_b64_tr_b16 v[126:127], v218 offset:8704
	v_mfma_f32_32x32x16_bf16 v[52:67], v[28:31], v[12:15], v[52:67]
	ds_read_b64_tr_b16 v[128:129], v218 offset:12288
	ds_read_b64_tr_b16 v[130:131], v218 offset:12800
	v_mfma_f32_32x32x16_bf16 v[52:67], v[32:35], v[16:19], v[52:67]
	ds_read_b64_tr_b16 v[132:133], v218 offset:1024
	ds_read_b64_tr_b16 v[134:135], v218 offset:1536
	v_mfma_f32_32x32x16_bf16 v[68:83], v[36:39], v[4:7], v[84:99]
	ds_read_b64_tr_b16 v[136:137], v218 offset:5120
	ds_read_b64_tr_b16 v[138:139], v218 offset:5632
	v_mfma_f32_32x32x16_bf16 v[68:83], v[40:43], v[8:11], v[68:83]
	ds_read_b64_tr_b16 v[140:141], v218 offset:9216
	ds_read_b64_tr_b16 v[142:143], v218 offset:9728
	v_mfma_f32_32x32x16_bf16 v[68:83], v[44:47], v[12:15], v[68:83]
	ds_read_b64_tr_b16 v[144:145], v218 offset:13312
	ds_read_b64_tr_b16 v[146:147], v218 offset:13824
	v_mfma_f32_32x32x16_bf16 v[68:83], v[48:51], v[16:19], v[68:83]
	s_nop 7
	s_nop 7
	v_max3_f32 v219, v52, v53, v54
	v_max3_f32 v220, v55, v56, v57
	v_max3_f32 v219, v219, v58, v59
	v_max3_f32 v220, v220, v60, v61
	v_max3_f32 v219, v219, v62, v63
	v_max3_f32 v220, v220, v64, v65
	v_max3_f32 v219, v219, v66, v67
	v_max3_f32 v220, v220, v68, v69
	v_max3_f32 v219, v219, v70, v71
	v_max3_f32 v220, v220, v72, v73
	v_max3_f32 v219, v219, v74, v75
	v_max3_f32 v220, v220, v76, v77
	v_max3_f32 v219, v219, v78, v79
	v_max3_f32 v220, v220, v80, v81
	v_max3_f32 v219, v219, v82, v83
	v_max_f32_e32 v214, v219, v220
	v_mov_b32_e32 v219, v214
	s_nop 1
	v_permlane32_swap_b32_e32 v214, v219
	v_max_f32_e32 v214, v214, v219
	s_mov_b32 s54, 0
	v_cmp_lt_f32_e32 vcc, s48, v214
	s_nop 0
	s_cmp_lg_u64 vcc, 0
	s_cbranch_scc0 .Lat_nores6
	v_max_f32_e32 v214, 0, v214
	v_add_f32_e32 v212, v212, v214
	v_sub_f32_e32 v52, v52, v214
	v_sub_f32_e32 v53, v53, v214
	v_sub_f32_e32 v54, v54, v214
	v_sub_f32_e32 v55, v55, v214
	v_sub_f32_e32 v56, v56, v214
	v_sub_f32_e32 v57, v57, v214
	v_sub_f32_e32 v58, v58, v214
	v_sub_f32_e32 v59, v59, v214
	v_sub_f32_e32 v60, v60, v214
	v_sub_f32_e32 v61, v61, v214
	v_sub_f32_e32 v62, v62, v214
	v_sub_f32_e32 v63, v63, v214
	v_sub_f32_e32 v64, v64, v214
	v_sub_f32_e32 v65, v65, v214
	v_sub_f32_e32 v66, v66, v214
	v_sub_f32_e32 v67, v67, v214
	v_sub_f32_e32 v68, v68, v214
	v_sub_f32_e32 v69, v69, v214
	v_sub_f32_e32 v70, v70, v214
	v_sub_f32_e32 v71, v71, v214
	v_sub_f32_e32 v72, v72, v214
	v_sub_f32_e32 v73, v73, v214
	v_sub_f32_e32 v74, v74, v214
	v_sub_f32_e32 v75, v75, v214
	v_sub_f32_e32 v76, v76, v214
	v_sub_f32_e32 v77, v77, v214
	v_sub_f32_e32 v78, v78, v214
	v_sub_f32_e32 v79, v79, v214
	v_sub_f32_e32 v80, v80, v214
	v_sub_f32_e32 v81, v81, v214
	v_sub_f32_e32 v82, v82, v214
	v_sub_f32_e32 v83, v83, v214
	v_xor_b32_e32 v84, 0x80000000, v212
	v_xor_b32_e32 v85, 0x80000000, v212
	v_xor_b32_e32 v86, 0x80000000, v212
	v_xor_b32_e32 v87, 0x80000000, v212
	v_xor_b32_e32 v88, 0x80000000, v212
	v_xor_b32_e32 v89, 0x80000000, v212
	v_xor_b32_e32 v90, 0x80000000, v212
	v_xor_b32_e32 v91, 0x80000000, v212
	v_xor_b32_e32 v92, 0x80000000, v212
	v_xor_b32_e32 v93, 0x80000000, v212
	v_xor_b32_e32 v94, 0x80000000, v212
	v_xor_b32_e32 v95, 0x80000000, v212
	v_xor_b32_e32 v96, 0x80000000, v212
	v_xor_b32_e32 v97, 0x80000000, v212
	v_xor_b32_e32 v98, 0x80000000, v212
	v_xor_b32_e32 v99, 0x80000000, v212
	v_exp_f32_e64 v215, -v214
	s_mov_b32 s54, 1
	v_add_u32_e32 v222, v230, v240
	v_mul_f32_e32 v213, v213, v215
	ds_write_b32 v222, v215 offset:0
.Lat_nores6:
	s_waitcnt lgkmcnt(0)
	v_mfma_f32_32x32x16_bf16 v[148:163], v[100:103], v[116:119], v[148:163]
	v_exp_f32_e32 v52, v52
	v_exp_f32_e32 v53, v53
	ds_read_b64_tr_b16 v[116:117], v218 offset:2048
	ds_read_b64_tr_b16 v[118:119], v218 offset:2560
	v_mfma_f32_32x32x16_bf16 v[164:179], v[100:103], v[120:123], v[164:179]
	v_exp_f32_e32 v54, v54
	v_exp_f32_e32 v55, v55
	ds_read_b64_tr_b16 v[120:121], v218 offset:6144
	ds_read_b64_tr_b16 v[122:123], v218 offset:6656
	v_add_f32_e32 v216, v52, v53
	v_mfma_f32_32x32x16_bf16 v[180:195], v[100:103], v[124:127], v[180:195]
	v_exp_f32_e32 v56, v56
	v_exp_f32_e32 v57, v57
	ds_read_b64_tr_b16 v[124:125], v218 offset:10240
	ds_read_b64_tr_b16 v[126:127], v218 offset:10752
	v_add_f32_e32 v216, v216, v54
	v_add_f32_e32 v216, v216, v55
	v_mfma_f32_32x32x16_bf16 v[196:211], v[100:103], v[128:131], v[196:211]
	v_exp_f32_e32 v58, v58
	v_exp_f32_e32 v59, v59
	ds_read_b64_tr_b16 v[128:129], v218 offset:14336
	ds_read_b64_tr_b16 v[130:131], v218 offset:14848
	v_add_f32_e32 v216, v216, v56
	v_add_f32_e32 v216, v216, v57
	v_mfma_f32_32x32x16_bf16 v[148:163], v[104:107], v[132:135], v[148:163]
	v_exp_f32_e32 v60, v60
	v_exp_f32_e32 v61, v61
	ds_read_b64_tr_b16 v[132:133], v218 offset:3072
	ds_read_b64_tr_b16 v[134:135], v218 offset:3584
	v_add_f32_e32 v216, v216, v58
	v_add_f32_e32 v216, v216, v59
	v_cvt_pk_bf16_f32 v100, v52, v53
	v_cvt_pk_bf16_f32 v101, v54, v55
	v_cvt_pk_bf16_f32 v102, v56, v57
	v_cvt_pk_bf16_f32 v103, v58, v59
	v_mfma_f32_32x32x16_bf16 v[164:179], v[104:107], v[136:139], v[164:179]
	v_exp_f32_e32 v62, v62
	v_exp_f32_e32 v63, v63
	ds_read_b64_tr_b16 v[136:137], v218 offset:7168
	ds_read_b64_tr_b16 v[138:139], v218 offset:7680
	v_add_f32_e32 v216, v216, v60
	v_add_f32_e32 v216, v216, v61
	v_mfma_f32_32x32x16_bf16 v[180:195], v[104:107], v[140:143], v[180:195]
	v_exp_f32_e32 v64, v64
	v_exp_f32_e32 v65, v65
	ds_read_b64_tr_b16 v[140:141], v218 offset:11264
	ds_read_b64_tr_b16 v[142:143], v218 offset:11776
	v_add_f32_e32 v216, v216, v62
	v_add_f32_e32 v216, v216, v63
	v_mfma_f32_32x32x16_bf16 v[196:211], v[104:107], v[144:147], v[196:211]
	v_exp_f32_e32 v66, v66
	v_exp_f32_e32 v67, v67
	ds_read_b64_tr_b16 v[144:145], v218 offset:15360
	ds_read_b64_tr_b16 v[146:147], v218 offset:15872
	v_add_f32_e32 v216, v216, v64
	v_add_f32_e32 v216, v216, v65
	s_waitcnt lgkmcnt(14)
	v_mfma_f32_32x32x16_bf16 v[148:163], v[108:111], v[116:119], v[148:163]
	v_exp_f32_e32 v68, v68
	v_exp_f32_e32 v69, v69
	v_add_u32_e32 v225, s26, v235
	ds_read_b128 v[20:23], v225
	v_add_f32_e32 v216, v216, v66
	v_add_f32_e32 v216, v216, v67
	v_cvt_pk_bf16_f32 v104, v60, v61
	v_cvt_pk_bf16_f32 v105, v62, v63
	v_cvt_pk_bf16_f32 v106, v64, v65
	v_cvt_pk_bf16_f32 v107, v66, v67
	s_waitcnt lgkmcnt(13)
	v_mfma_f32_32x32x16_bf16 v[164:179], v[108:111], v[120:123], v[164:179]
	v_exp_f32_e32 v70, v70
	v_exp_f32_e32 v71, v71
	v_add_u32_e32 v226, s26, v236
	ds_read_b128 v[24:27], v226
	v_add_f32_e32 v216, v216, v68
	v_add_f32_e32 v216, v216, v69
	s_waitcnt lgkmcnt(12)
	v_mfma_f32_32x32x16_bf16 v[180:195], v[108:111], v[124:127], v[180:195]
	v_exp_f32_e32 v72, v72
	v_exp_f32_e32 v73, v73
	v_add_u32_e32 v227, s26, v237
	ds_read_b128 v[28:31], v227
	v_add_f32_e32 v216, v216, v70
	v_add_f32_e32 v216, v216, v71
	s_waitcnt lgkmcnt(11)
	v_mfma_f32_32x32x16_bf16 v[196:211], v[108:111], v[128:131], v[196:211]
	v_exp_f32_e32 v74, v74
	v_exp_f32_e32 v75, v75
	v_add_u32_e32 v228, s26, v238
	ds_read_b128 v[32:35], v228
	v_add_f32_e32 v216, v216, v72
	v_add_f32_e32 v216, v216, v73
	s_waitcnt lgkmcnt(10)
	v_mfma_f32_32x32x16_bf16 v[148:163], v[112:115], v[132:135], v[148:163]
	v_exp_f32_e32 v76, v76
	v_exp_f32_e32 v77, v77
	ds_read_b128 v[36:39], v225 offset:4096
	v_add_f32_e32 v216, v216, v74
	v_add_f32_e32 v216, v216, v75
	v_cvt_pk_bf16_f32 v108, v68, v69
	v_cvt_pk_bf16_f32 v109, v70, v71
	v_cvt_pk_bf16_f32 v110, v72, v73
	v_cvt_pk_bf16_f32 v111, v74, v75
	s_waitcnt lgkmcnt(9)
	v_mfma_f32_32x32x16_bf16 v[164:179], v[112:115], v[136:139], v[164:179]
	v_exp_f32_e32 v78, v78
	v_exp_f32_e32 v79, v79
	ds_read_b128 v[40:43], v226 offset:4096
	v_add_f32_e32 v216, v216, v76
	v_add_f32_e32 v216, v216, v77
	s_waitcnt lgkmcnt(8)
	v_mfma_f32_32x32x16_bf16 v[180:195], v[112:115], v[140:143], v[180:195]
	v_exp_f32_e32 v80, v80
	v_exp_f32_e32 v81, v81
	ds_read_b128 v[44:47], v227 offset:4096
	v_add_f32_e32 v216, v216, v78
	v_add_f32_e32 v216, v216, v79
	s_waitcnt lgkmcnt(7)
	v_mfma_f32_32x32x16_bf16 v[196:211], v[112:115], v[144:147], v[196:211]
	v_exp_f32_e32 v82, v82
	v_exp_f32_e32 v83, v83
	ds_read_b128 v[48:51], v228 offset:4096
	v_add_f32_e32 v216, v216, v80
	v_add_f32_e32 v216, v216, v81
	v_add_f32_e32 v216, v216, v82
	v_add_f32_e32 v216, v216, v83
	v_cvt_pk_bf16_f32 v112, v76, v77
	v_cvt_pk_bf16_f32 v113, v78, v79
	v_cvt_pk_bf16_f32 v114, v80, v81
	v_cvt_pk_bf16_f32 v115, v82, v83
	v_add_f32_e32 v213, v213, v216
	s_branch .Lat_end5
;   #define CMASK(P0,P1,t) do{int jb_=(t)-(NT-4); if(jb_>=0)cmask(P0,P1,jb_,vlim);}while(0)
;   #define START(P0,P1) do{ const float rm=rowmax(P0,P1); resc=false; \
;     { const float dl=rm; mhat=fadd_s(mhat,dl); \
;       _Pragma("unroll") for(int r=0;r<16;++r){P0[r]=fsub_s(P0[r],dl);P1[r]=fsub_s(P1[r],dl);} \
;       _Pragma("unroll") for(int r=0;r<16;++r)negm[r]=-mhat; asm volatile("":"+v"(negm)); } \
;     _Pragma("unroll") for(int r=0;r<16;++r)P0[r]=__builtin_amdgcn_exp2f(P0[r]); }while(0)
;   #define CMASK(P0,P1,t) do{}while(0)
;   #define CMASK(P0,P1,t) do{int jb_=(t)-(NT-4); if(jb_>=0)cmask(P0,P1,jb_,vlim);}while(0)
; template<int THRL,bool PART> __device__ __forceinline__ int attn_unit(const bf16*Qb,const bf16*__restrict__ Kh,const bf16*__restrict__ Vh,bf16*Ob,const int NT,const int vlim_in,char*shm,const int s0,const bool primed,const bf16*nKh,const bf16*nVh,bf16*fuseM,const float lam){
;     ...
;   if(act){
;   qkt(pA0,pA1,Kbase,qr,negm,r32,hi);asm volatile("s_nop 15\n\ts_nop 7":"+v"(pA0),"+v"(pA1));CMASK(pA0,pA1,0);
;   START(pA0,pA1);
;   _Pragma("unroll") for(int r=0;r<16;++r)pA1[r]=__builtin_amdgcn_exp2f(pA1[r]);
;   }
.Lat_first3:
	s_waitcnt lgkmcnt(0)
	v_mfma_f32_32x32x16_bf16 v[52:67], v[20:23], v[4:7], v[84:99]
	v_mfma_f32_32x32x16_bf16 v[52:67], v[24:27], v[8:11], v[52:67]
	v_mfma_f32_32x32x16_bf16 v[52:67], v[28:31], v[12:15], v[52:67]
	v_mfma_f32_32x32x16_bf16 v[52:67], v[32:35], v[16:19], v[52:67]
	v_mfma_f32_32x32x16_bf16 v[68:83], v[36:39], v[4:7], v[84:99]
	v_mfma_f32_32x32x16_bf16 v[68:83], v[40:43], v[8:11], v[68:83]
	v_mfma_f32_32x32x16_bf16 v[68:83], v[44:47], v[12:15], v[68:83]
	v_mfma_f32_32x32x16_bf16 v[68:83], v[48:51], v[16:19], v[68:83]
	s_nop 7
	s_nop 7
	v_max3_f32 v219, v52, v53, v54
	v_max3_f32 v220, v55, v56, v57
	v_max3_f32 v219, v219, v58, v59
	v_max3_f32 v220, v220, v60, v61
	v_max3_f32 v219, v219, v62, v63
	v_max3_f32 v220, v220, v64, v65
	v_max3_f32 v219, v219, v66, v67
	v_max3_f32 v220, v220, v68, v69
	v_max3_f32 v219, v219, v70, v71
	v_max3_f32 v220, v220, v72, v73
	v_max3_f32 v219, v219, v74, v75
	v_max3_f32 v220, v220, v76, v77
	v_max3_f32 v219, v219, v78, v79
	v_max3_f32 v220, v220, v80, v81
	v_max3_f32 v219, v219, v82, v83
	v_max_f32_e32 v214, v219, v220
	v_mov_b32_e32 v219, v214
	s_nop 1
	v_permlane32_swap_b32_e32 v214, v219
	v_max_f32_e32 v214, v214, v219
	s_mov_b32 s54, 0
	v_mov_b32_e32 v212, v214
	v_sub_f32_e32 v52, v52, v214
	v_sub_f32_e32 v53, v53, v214
	v_sub_f32_e32 v54, v54, v214
	v_sub_f32_e32 v55, v55, v214
	v_sub_f32_e32 v56, v56, v214
	v_sub_f32_e32 v57, v57, v214
	v_sub_f32_e32 v58, v58, v214
	v_sub_f32_e32 v59, v59, v214
	v_sub_f32_e32 v60, v60, v214
	v_sub_f32_e32 v61, v61, v214
	v_sub_f32_e32 v62, v62, v214
	v_sub_f32_e32 v63, v63, v214
	v_sub_f32_e32 v64, v64, v214
	v_sub_f32_e32 v65, v65, v214
	v_sub_f32_e32 v66, v66, v214
	v_sub_f32_e32 v67, v67, v214
	v_sub_f32_e32 v68, v68, v214
	v_sub_f32_e32 v69, v69, v214
	v_sub_f32_e32 v70, v70, v214
	v_sub_f32_e32 v71, v71, v214
	v_sub_f32_e32 v72, v72, v214
	v_sub_f32_e32 v73, v73, v214
	v_sub_f32_e32 v74, v74, v214
	v_sub_f32_e32 v75, v75, v214
	v_sub_f32_e32 v76, v76, v214
	v_sub_f32_e32 v77, v77, v214
	v_sub_f32_e32 v78, v78, v214
	v_sub_f32_e32 v79, v79, v214
	v_sub_f32_e32 v80, v80, v214
	v_sub_f32_e32 v81, v81, v214
	v_sub_f32_e32 v82, v82, v214
	v_sub_f32_e32 v83, v83, v214
	v_xor_b32_e32 v84, 0x80000000, v212
	v_xor_b32_e32 v85, 0x80000000, v212
	v_xor_b32_e32 v86, 0x80000000, v212
	v_xor_b32_e32 v87, 0x80000000, v212
	v_xor_b32_e32 v88, 0x80000000, v212
	v_xor_b32_e32 v89, 0x80000000, v212
	v_xor_b32_e32 v90, 0x80000000, v212
	v_xor_b32_e32 v91, 0x80000000, v212
	v_xor_b32_e32 v92, 0x80000000, v212
	v_xor_b32_e32 v93, 0x80000000, v212
	v_xor_b32_e32 v94, 0x80000000, v212
	v_xor_b32_e32 v95, 0x80000000, v212
	v_xor_b32_e32 v96, 0x80000000, v212
	v_xor_b32_e32 v97, 0x80000000, v212
	v_xor_b32_e32 v98, 0x80000000, v212
	v_xor_b32_e32 v99, 0x80000000, v212
	v_add_u32_e32 v225, s26, v235
	ds_read_b128 v[20:23], v225
	v_add_u32_e32 v226, s26, v236
	ds_read_b128 v[24:27], v226
	v_add_u32_e32 v227, s26, v237
	ds_read_b128 v[28:31], v227
	v_add_u32_e32 v228, s26, v238
	ds_read_b128 v[32:35], v228
	ds_read_b128 v[36:39], v225 offset:4096
	ds_read_b128 v[40:43], v226 offset:4096
	ds_read_b128 v[44:47], v227 offset:4096
	ds_read_b128 v[48:51], v228 offset:4096
	v_exp_f32_e32 v52, v52
	v_exp_f32_e32 v53, v53
	v_exp_f32_e32 v54, v54
	v_exp_f32_e32 v55, v55
	v_exp_f32_e32 v56, v56
	v_exp_f32_e32 v57, v57
	v_exp_f32_e32 v58, v58
	v_exp_f32_e32 v59, v59
	v_exp_f32_e32 v60, v60
	v_exp_f32_e32 v61, v61
	v_exp_f32_e32 v62, v62
	v_exp_f32_e32 v63, v63
	v_exp_f32_e32 v64, v64
	v_exp_f32_e32 v65, v65
	v_exp_f32_e32 v66, v66
	v_exp_f32_e32 v67, v67
	v_exp_f32_e32 v68, v68
	v_exp_f32_e32 v69, v69
	v_exp_f32_e32 v70, v70
	v_exp_f32_e32 v71, v71
	v_exp_f32_e32 v72, v72
	v_exp_f32_e32 v73, v73
	v_exp_f32_e32 v74, v74
	v_exp_f32_e32 v75, v75
	v_exp_f32_e32 v76, v76
	v_exp_f32_e32 v77, v77
	v_exp_f32_e32 v78, v78
	v_exp_f32_e32 v79, v79
	v_exp_f32_e32 v80, v80
	v_exp_f32_e32 v81, v81
	v_exp_f32_e32 v82, v82
	v_exp_f32_e32 v83, v83
	v_add_f32_e32 v216, v52, v53
	v_add_f32_e32 v216, v216, v54
	v_add_f32_e32 v216, v216, v55
	v_add_f32_e32 v216, v216, v56
	v_add_f32_e32 v216, v216, v57
	v_add_f32_e32 v216, v216, v58
	v_add_f32_e32 v216, v216, v59
	v_add_f32_e32 v216, v216, v60
	v_add_f32_e32 v216, v216, v61
	v_add_f32_e32 v216, v216, v62
	v_add_f32_e32 v216, v216, v63
	v_add_f32_e32 v216, v216, v64
	v_add_f32_e32 v216, v216, v65
	v_add_f32_e32 v216, v216, v66
	v_add_f32_e32 v216, v216, v67
	v_add_f32_e32 v216, v216, v68
	v_add_f32_e32 v216, v216, v69
	v_add_f32_e32 v216, v216, v70
	v_add_f32_e32 v216, v216, v71
	v_add_f32_e32 v216, v216, v72
	v_add_f32_e32 v216, v216, v73
	v_add_f32_e32 v216, v216, v74
	v_add_f32_e32 v216, v216, v75
	v_add_f32_e32 v216, v216, v76
	v_add_f32_e32 v216, v216, v77
	v_add_f32_e32 v216, v216, v78
	v_add_f32_e32 v216, v216, v79
	v_add_f32_e32 v216, v216, v80
	v_add_f32_e32 v216, v216, v81
	v_add_f32_e32 v216, v216, v82
	v_add_f32_e32 v216, v216, v83
	v_cvt_pk_bf16_f32 v100, v52, v53
	v_cvt_pk_bf16_f32 v101, v54, v55
	v_cvt_pk_bf16_f32 v102, v56, v57
	v_cvt_pk_bf16_f32 v103, v58, v59
	v_cvt_pk_bf16_f32 v104, v60, v61
	v_cvt_pk_bf16_f32 v105, v62, v63
	v_cvt_pk_bf16_f32 v106, v64, v65
	v_cvt_pk_bf16_f32 v107, v66, v67
	v_cvt_pk_bf16_f32 v108, v68, v69
	v_cvt_pk_bf16_f32 v109, v70, v71
	v_cvt_pk_bf16_f32 v110, v72, v73
	v_cvt_pk_bf16_f32 v111, v74, v75
	v_cvt_pk_bf16_f32 v112, v76, v77
	v_cvt_pk_bf16_f32 v113, v78, v79
	v_cvt_pk_bf16_f32 v114, v80, v81
	v_cvt_pk_bf16_f32 v115, v82, v83
	v_add_f32_e32 v213, v213, v216
	s_branch .Lat_end5
; #define SBAR() __builtin_amdgcn_sched_barrier(0)
;   #define RESC() do{ if(resc){ asm volatile("s_waitcnt lgkmcnt(0)":::"memory"); \
;       _Pragma("unroll") for(int d_=0;d_<2;++d_) _Pragma("unroll") for(int r=0;r<16;++r)o[d_][r]*=wsf[crow(r,hi)]; } }while(0)
;   #define PKW(P,B) cvtpk_s(P[B],P[B+1])
; template<int THRL,bool PART> __device__ __forceinline__ int attn_unit(const bf16*Qb,const bf16*__restrict__ Kh,const bf16*__restrict__ Vh,bf16*Ob,const int NT,const int vlim_in,char*shm,const int s0,const bool primed,const bf16*nKh,const bf16*nVh,bf16*fuseM,const float lam){
;     ...
;   STEP(pB0,pB1,pA0,pA1,NT-1,false,false,false); RESC();
;   if(act){ float sacc=pB0[0]+pB0[1]; _Pragma("unroll") for(int r=2;r<16;++r)sacc+=pB0[r]; _Pragma("unroll") for(int r=0;r<16;++r)sacc+=pB1[r]; l_reg+=sacc;
;     pw0=(u32x4){PKW(pB0,0),PKW(pB0,2),PKW(pB0,4),PKW(pB0,6)};pw1=(u32x4){PKW(pB0,8),PKW(pB0,10),PKW(pB0,12),PKW(pB0,14)};pw2=(u32x4){PKW(pB1,0),PKW(pB1,2),PKW(pB1,4),PKW(pB1,6)};pw3=(u32x4){PKW(pB1,8),PKW(pB1,10),PKW(pB1,12),PKW(pB1,14)};
;     SBAR(); pv(o,vb0+sl_cur,PAF(0),PAF(1),PAF(2),PAF(3)); }
.Lat_last4:
	s_mov_b32 s54, 0
	s_cmp_eq_u32 s17, s16
	s_cbranch_scc0 .Lat_end5
	v_add_u32_e32 v218, s28, v229
	ds_read_b64_tr_b16 v[116:117], v218 offset:0
	ds_read_b64_tr_b16 v[118:119], v218 offset:512
	ds_read_b64_tr_b16 v[120:121], v218 offset:4096
	ds_read_b64_tr_b16 v[122:123], v218 offset:4608
	ds_read_b64_tr_b16 v[124:125], v218 offset:8192
	ds_read_b64_tr_b16 v[126:127], v218 offset:8704
	ds_read_b64_tr_b16 v[128:129], v218 offset:12288
	ds_read_b64_tr_b16 v[130:131], v218 offset:12800
	ds_read_b64_tr_b16 v[132:133], v218 offset:1024
	ds_read_b64_tr_b16 v[134:135], v218 offset:1536
	ds_read_b64_tr_b16 v[136:137], v218 offset:5120
	ds_read_b64_tr_b16 v[138:139], v218 offset:5632
	ds_read_b64_tr_b16 v[140:141], v218 offset:9216
	ds_read_b64_tr_b16 v[142:143], v218 offset:9728
	ds_read_b64_tr_b16 v[144:145], v218 offset:13312
	ds_read_b64_tr_b16 v[146:147], v218 offset:13824
	s_waitcnt lgkmcnt(0)
	v_mfma_f32_32x32x16_bf16 v[148:163], v[100:103], v[116:119], v[148:163]
	ds_read_b64_tr_b16 v[116:117], v218 offset:2048
	ds_read_b64_tr_b16 v[118:119], v218 offset:2560
	v_mfma_f32_32x32x16_bf16 v[164:179], v[100:103], v[120:123], v[164:179]
	ds_read_b64_tr_b16 v[120:121], v218 offset:6144
	ds_read_b64_tr_b16 v[122:123], v218 offset:6656
	v_mfma_f32_32x32x16_bf16 v[180:195], v[100:103], v[124:127], v[180:195]
	ds_read_b64_tr_b16 v[124:125], v218 offset:10240
	ds_read_b64_tr_b16 v[126:127], v218 offset:10752
	v_mfma_f32_32x32x16_bf16 v[196:211], v[100:103], v[128:131], v[196:211]
	ds_read_b64_tr_b16 v[128:129], v218 offset:14336
	ds_read_b64_tr_b16 v[130:131], v218 offset:14848
	v_mfma_f32_32x32x16_bf16 v[148:163], v[104:107], v[132:135], v[148:163]
	ds_read_b64_tr_b16 v[132:133], v218 offset:3072
	ds_read_b64_tr_b16 v[134:135], v218 offset:3584
	v_mfma_f32_32x32x16_bf16 v[164:179], v[104:107], v[136:139], v[164:179]
	ds_read_b64_tr_b16 v[136:137], v218 offset:7168
	ds_read_b64_tr_b16 v[138:139], v218 offset:7680
	v_mfma_f32_32x32x16_bf16 v[180:195], v[104:107], v[140:143], v[180:195]
	ds_read_b64_tr_b16 v[140:141], v218 offset:11264
	ds_read_b64_tr_b16 v[142:143], v218 offset:11776
	v_mfma_f32_32x32x16_bf16 v[196:211], v[104:107], v[144:147], v[196:211]
	ds_read_b64_tr_b16 v[144:145], v218 offset:15360
	ds_read_b64_tr_b16 v[146:147], v218 offset:15872
	s_waitcnt lgkmcnt(14)
	v_mfma_f32_32x32x16_bf16 v[148:163], v[108:111], v[116:119], v[148:163]
	s_waitcnt lgkmcnt(12)
	v_mfma_f32_32x32x16_bf16 v[164:179], v[108:111], v[120:123], v[164:179]
	s_waitcnt lgkmcnt(10)
	v_mfma_f32_32x32x16_bf16 v[180:195], v[108:111], v[124:127], v[180:195]
	s_waitcnt lgkmcnt(8)
	v_mfma_f32_32x32x16_bf16 v[196:211], v[108:111], v[128:131], v[196:211]
	s_waitcnt lgkmcnt(6)
	v_mfma_f32_32x32x16_bf16 v[148:163], v[112:115], v[132:135], v[148:163]
	s_waitcnt lgkmcnt(4)
	v_mfma_f32_32x32x16_bf16 v[164:179], v[112:115], v[136:139], v[164:179]
	s_waitcnt lgkmcnt(2)
	v_mfma_f32_32x32x16_bf16 v[180:195], v[112:115], v[140:143], v[180:195]
	s_waitcnt lgkmcnt(0)
	v_mfma_f32_32x32x16_bf16 v[196:211], v[112:115], v[144:147], v[196:211]
.Lat_end5:
	s_cmp_eq_u32 s54, 0
	s_cbranch_scc1 .Lat_nor7
	s_nop 7
	s_nop 7
	v_add_u32_e32 v222, v230, v241
	ds_read_b128 v[116:119], v222 offset:0
	ds_read_b128 v[120:123], v222 offset:32
	ds_read_b128 v[124:127], v222 offset:64
	ds_read_b128 v[128:131], v222 offset:96
	s_waitcnt lgkmcnt(0)
	v_mul_f32_e32 v148, v148, v116
	v_mul_f32_e32 v149, v149, v117
	v_mul_f32_e32 v150, v150, v118
	v_mul_f32_e32 v151, v151, v119
	v_mul_f32_e32 v152, v152, v120
	v_mul_f32_e32 v153, v153, v121
	v_mul_f32_e32 v154, v154, v122
	v_mul_f32_e32 v155, v155, v123
	v_mul_f32_e32 v156, v156, v124
	v_mul_f32_e32 v157, v157, v125
	v_mul_f32_e32 v158, v158, v126
	v_mul_f32_e32 v159, v159, v127
	v_mul_f32_e32 v160, v160, v128
	v_mul_f32_e32 v161, v161, v129
	v_mul_f32_e32 v162, v162, v130
	v_mul_f32_e32 v163, v163, v131
	v_mul_f32_e32 v164, v164, v116
	v_mul_f32_e32 v165, v165, v117
	v_mul_f32_e32 v166, v166, v118
	v_mul_f32_e32 v167, v167, v119
	v_mul_f32_e32 v168, v168, v120
	v_mul_f32_e32 v169, v169, v121
	v_mul_f32_e32 v170, v170, v122
	v_mul_f32_e32 v171, v171, v123
	v_mul_f32_e32 v172, v172, v124
	v_mul_f32_e32 v173, v173, v125
	v_mul_f32_e32 v174, v174, v126
	v_mul_f32_e32 v175, v175, v127
	v_mul_f32_e32 v176, v176, v128
	v_mul_f32_e32 v177, v177, v129
	v_mul_f32_e32 v178, v178, v130
	v_mul_f32_e32 v179, v179, v131
	v_mul_f32_e32 v180, v180, v116
	v_mul_f32_e32 v181, v181, v117
	v_mul_f32_e32 v182, v182, v118
	v_mul_f32_e32 v183, v183, v119
	v_mul_f32_e32 v184, v184, v120
	v_mul_f32_e32 v185, v185, v121
	v_mul_f32_e32 v186, v186, v122
	v_mul_f32_e32 v187, v187, v123
	v_mul_f32_e32 v188, v188, v124
	v_mul_f32_e32 v189, v189, v125
	v_mul_f32_e32 v190, v190, v126
	v_mul_f32_e32 v191, v191, v127
	v_mul_f32_e32 v192, v192, v128
	v_mul_f32_e32 v193, v193, v129
	v_mul_f32_e32 v194, v194, v130
	v_mul_f32_e32 v195, v195, v131
	v_mul_f32_e32 v196, v196, v116
	v_mul_f32_e32 v197, v197, v117
	v_mul_f32_e32 v198, v198, v118
	v_mul_f32_e32 v199, v199, v119
	v_mul_f32_e32 v200, v200, v120
	v_mul_f32_e32 v201, v201, v121
	v_mul_f32_e32 v202, v202, v122
	v_mul_f32_e32 v203, v203, v123
	v_mul_f32_e32 v204, v204, v124
	v_mul_f32_e32 v205, v205, v125
	v_mul_f32_e32 v206, v206, v126
	v_mul_f32_e32 v207, v207, v127
	v_mul_f32_e32 v208, v208, v128
	v_mul_f32_e32 v209, v209, v129
	v_mul_f32_e32 v210, v210, v130
	v_mul_f32_e32 v211, v211, v131
.Lat_nor7:
	s_add_i32 s34, s17, 4
	s_cmp_lt_u32 s34, s15
	s_cbranch_scc0 .Lat_dn8
	s_lshl_b32 s37, s4, 10
	s_add_i32 m0, s37, s27
	s_nop 0
	global_load_lds_dwordx4 v231, s[18:19]
	s_add_u32 s18, s18, 0x10000
	s_addc_u32 s19, s19, 0
	s_lshl_b32 s37, s4, 10
	s_add_i32 m0, s37, s29
	s_nop 0
	global_load_lds_dwordx4 v232, s[20:21]
	s_add_i32 m0, m0, 0x2000
	s_nop 0
	global_load_lds_dwordx4 v233, s[20:21]
	s_add_u32 s20, s20, 0x10000
	s_addc_u32 s21, s21, 0
	s_waitcnt vmcnt(6) lgkmcnt(0)
	s_branch .Lat_bar9
.Lat_dn8:
	s_add_i32 s34, s17, 2
	s_cmp_lt_u32 s34, s15
	s_cbranch_scc0 .Lat_dv10
	s_lshl_b32 s37, s4, 10
	s_add_i32 m0, s37, s29
	s_nop 0
	global_load_lds_dwordx4 v232, s[20:21]
	s_add_i32 m0, m0, 0x2000
	s_nop 0
	global_load_lds_dwordx4 v233, s[20:21]
	s_add_u32 s20, s20, 0x10000
	s_addc_u32 s21, s21, 0

; __device__ __forceinline__ int crow(int r,int hi){return (r&3)+8*(r>>2)+4*hi;}
; template<int THRL,bool PART> __device__ __forceinline__ int attn_unit(const bf16*Qb,const bf16*__restrict__ Kh,const bf16*__restrict__ Vh,bf16*Ob,const int NT,const int vlim_in,char*shm,const int s0,const bool primed,const bf16*nKh,const bf16*nVh,bf16*fuseM,const float lam){
;     ...
;   if(act){
;   {auto rr=__builtin_amdgcn_permlane32_swap(__float_as_uint(l_reg),__float_as_uint(l_reg),false,false);l_reg=__uint_as_float(rr[0])+__uint_as_float(rr[1]);}
;   if(hi==0)wsf[32+r32]=l_reg;asm volatile("s_waitcnt lgkmcnt(0)":::"memory");
;   float rli[16];
;   #pragma unroll
;   for(int r=0;r<16;++r)rli[r]=__builtin_amdgcn_rcpf(wsf[32+crow(r,hi)]);
;   bf16*Ow=Ob+(long)(wid*QBLK)*OP;
;   { bf16*stg=(bf16*)(shm+LDS_OST)+wid*2048;
;     #pragma unroll
;     for(int r=0;r<16;++r){const int orow=crow(r,hi);
;       #pragma unroll
;       for(int d0=0;d0<2;++d0)stg[orow*64+d0*32+r32]=__float2bfloat16(o[d0][r]*rli[r]);}
;     ...
;     if(!fuseM){
;     #pragma unroll
;     for(int i=0;i<4;++i){const int row=i*8+(lane>>3),ch=lane&7; const u32x4 v=*(const u32x4*)(stg+row*64+ch*8); ATTN_STORE16(Ow+(long)row*OP+ch*8,v);}
.Lat_bar9:
	s_barrier
	s_add_i32 s24, s24, 1
	s_and_b32 s24, s24, 3
	s_add_i32 s17, s17, 1
	s_cmp_le_u32 s17, s15
	s_cbranch_scc1 .Lat_t1
	v_add_u32_e32 v224, 0x1000, v239
	v_add_u32_e32 v225, 0x2000, v239
	v_add_u32_e32 v226, 0x3000, v239
	s_cmp_eq_u32 s14, 0
	s_cbranch_scc1 .Lat_nopre13
	global_load_dwordx4 v[20:23], v239, s[52:53] sc1
	global_load_dwordx4 v[24:27], v239, s[52:53] offset:1024 sc1
	global_load_dwordx4 v[28:31], v239, s[52:53] offset:2048 sc1
	global_load_dwordx4 v[32:35], v239, s[52:53] offset:3072 sc1
	global_load_dwordx4 v[36:39], v224, s[52:53] sc1
	global_load_dwordx4 v[40:43], v224, s[52:53] offset:1024 sc1
	global_load_dwordx4 v[44:47], v224, s[52:53] offset:2048 sc1
	global_load_dwordx4 v[48:51], v224, s[52:53] offset:3072 sc1
	global_load_dwordx4 v[52:55], v225, s[52:53] sc1
	global_load_dwordx4 v[56:59], v225, s[52:53] offset:1024 sc1
	global_load_dwordx4 v[60:63], v225, s[52:53] offset:2048 sc1
	global_load_dwordx4 v[64:67], v225, s[52:53] offset:3072 sc1
	global_load_dwordx4 v[68:71], v226, s[52:53] sc1
	global_load_dwordx4 v[72:75], v226, s[52:53] offset:1024 sc1
	global_load_dwordx4 v[76:79], v226, s[52:53] offset:2048 sc1
	global_load_dwordx4 v[80:83], v226, s[52:53] offset:3072 sc1
.Lat_nopre13:
	v_mov_b32_e32 v219, v213
	s_nop 1
	v_permlane32_swap_b32_e32 v213, v219
	v_add_f32_e32 v213, v213, v219
	v_rcp_f32_e32 v220, v213
	v_add_u32_e32 v222, v230, v240
	s_nop 0
	ds_write_b32 v222, v220 offset:384
	s_waitcnt lgkmcnt(0)
	s_nop 7
	s_nop 7
	v_add_u32_e32 v222, v230, v241
	ds_read_b128 v[116:119], v222 offset:384
	ds_read_b128 v[120:123], v222 offset:416
	ds_read_b128 v[124:127], v222 offset:448
	ds_read_b128 v[128:131], v222 offset:480
	s_waitcnt lgkmcnt(0)
	v_mul_f32_e32 v148, v148, v116
	v_mul_f32_e32 v149, v149, v117
	v_mul_f32_e32 v150, v150, v118
	v_mul_f32_e32 v151, v151, v119
	v_mul_f32_e32 v152, v152, v120
	v_mul_f32_e32 v153, v153, v121
	v_mul_f32_e32 v154, v154, v122
	v_mul_f32_e32 v155, v155, v123
	v_mul_f32_e32 v156, v156, v124
	v_mul_f32_e32 v157, v157, v125
	v_mul_f32_e32 v158, v158, v126
	v_mul_f32_e32 v159, v159, v127
	v_mul_f32_e32 v160, v160, v128
	v_mul_f32_e32 v161, v161, v129
	v_mul_f32_e32 v162, v162, v130
	v_mul_f32_e32 v163, v163, v131
	v_mul_f32_e32 v164, v164, v116
	v_mul_f32_e32 v165, v165, v117
	v_mul_f32_e32 v166, v166, v118
	v_mul_f32_e32 v167, v167, v119
	v_mul_f32_e32 v168, v168, v120
	v_mul_f32_e32 v169, v169, v121
	v_mul_f32_e32 v170, v170, v122
	v_mul_f32_e32 v171, v171, v123
	v_mul_f32_e32 v172, v172, v124
	v_mul_f32_e32 v173, v173, v125
	v_mul_f32_e32 v174, v174, v126
	v_mul_f32_e32 v175, v175, v127
	v_mul_f32_e32 v176, v176, v128
	v_mul_f32_e32 v177, v177, v129
	v_mul_f32_e32 v178, v178, v130
	v_mul_f32_e32 v179, v179, v131
	v_mul_f32_e32 v180, v180, v116
	v_mul_f32_e32 v181, v181, v117
	v_mul_f32_e32 v182, v182, v118
	v_mul_f32_e32 v183, v183, v119
	v_mul_f32_e32 v184, v184, v120
	v_mul_f32_e32 v185, v185, v121
	v_mul_f32_e32 v186, v186, v122
	v_mul_f32_e32 v187, v187, v123
	v_mul_f32_e32 v188, v188, v124
	v_mul_f32_e32 v189, v189, v125
	v_mul_f32_e32 v190, v190, v126
	v_mul_f32_e32 v191, v191, v127
	v_mul_f32_e32 v192, v192, v128
	v_mul_f32_e32 v193, v193, v129
	v_mul_f32_e32 v194, v194, v130
	v_mul_f32_e32 v195, v195, v131
	v_mul_f32_e32 v196, v196, v116
	v_mul_f32_e32 v197, v197, v117
	v_mul_f32_e32 v198, v198, v118
	v_mul_f32_e32 v199, v199, v119
	v_mul_f32_e32 v200, v200, v120
	v_mul_f32_e32 v201, v201, v121
	v_mul_f32_e32 v202, v202, v122
	v_mul_f32_e32 v203, v203, v123
	v_mul_f32_e32 v204, v204, v124
	v_mul_f32_e32 v205, v205, v125
	v_mul_f32_e32 v206, v206, v126
	v_mul_f32_e32 v207, v207, v127
	v_mul_f32_e32 v208, v208, v128
	v_mul_f32_e32 v209, v209, v129
	v_mul_f32_e32 v210, v210, v130
	v_mul_f32_e32 v211, v211, v131
	s_cmp_lg_u32 s14, 0
	s_cbranch_scc1 .Lat_comb11
	global_store_dwordx4 v239, v[148:151], s[52:53]
	global_store_dwordx4 v239, v[152:155], s[52:53] offset:1024
	global_store_dwordx4 v239, v[156:159], s[52:53] offset:2048
	global_store_dwordx4 v239, v[160:163], s[52:53] offset:3072
	global_store_dwordx4 v224, v[164:167], s[52:53]
	global_store_dwordx4 v224, v[168:171], s[52:53] offset:1024
	global_store_dwordx4 v224, v[172:175], s[52:53] offset:2048
	global_store_dwordx4 v224, v[176:179], s[52:53] offset:3072
	global_store_dwordx4 v225, v[180:183], s[52:53]
	global_store_dwordx4 v225, v[184:187], s[52:53] offset:1024
	global_store_dwordx4 v225, v[188:191], s[52:53] offset:2048
	global_store_dwordx4 v225, v[192:195], s[52:53] offset:3072
	global_store_dwordx4 v226, v[196:199], s[52:53]
	global_store_dwordx4 v226, v[200:203], s[52:53] offset:1024
	global_store_dwordx4 v226, v[204:207], s[52:53] offset:2048
	global_store_dwordx4 v226, v[208:211], s[52:53] offset:3072
	s_branch .Lat_udone12
; __device__ __forceinline__ unsigned cvtpk_s(float lo,float hi){f32x2_t v={lo,hi};bf16x2_t b=__builtin_convertvector(v,bf16x2_t);return __builtin_bit_cast(unsigned,b);}
; template<int THRL,bool PART> __device__ __forceinline__ int attn_unit(const bf16*Qb,const bf16*__restrict__ Kh,const bf16*__restrict__ Vh,bf16*Ob,const int NT,const int vlim_in,char*shm,const int s0,const bool primed,const bf16*nKh,const bf16*nVh,bf16*fuseM,const float lam){
;     ...
;     asm volatile("s_waitcnt vmcnt(0)":::"memory"); __builtin_amdgcn_fence(__ATOMIC_ACQUIRE,"agent");
;     bf16*Mw=fuseM+(long)(wid*QBLK)*OP;
;     #pragma unroll
;     for(int i=0;i<4;++i){const int row=i*8+(lane>>3),ch=lane&7; const u32x4 v=*(const u32x4*)(stg+row*64+ch*8);
;       const bf16*gp=Ow+(long)row*OP+ch*8; const u32x4 a=*(const u32x4*)(gp-192), c1=*(const u32x4*)(gp-128), b=*(const u32x4*)(gp-64);
;       float d0[8],d1[8],ss=0.f;
;       #pragma unroll
;       for(int q=0;q<4;++q){ d0[2*q]=__uint_as_float(a[q]<<16)-lam*__uint_as_float(b[q]<<16); d0[2*q+1]=__uint_as_float(a[q]&0xffff0000u)-lam*__uint_as_float(b[q]&0xffff0000u);
;         d1[2*q]=__uint_as_float(c1[q]<<16)-lam*__uint_as_float(v[q]<<16); d1[2*q+1]=__uint_as_float(c1[q]&0xffff0000u)-lam*__uint_as_float(v[q]&0xffff0000u);
;         ss+=d0[2*q]*d0[2*q]+d0[2*q+1]*d0[2*q+1]+d1[2*q]*d1[2*q]+d1[2*q+1]*d1[2*q+1]; }
;       ss+=__shfl_xor(ss,1); ss+=__shfl_xor(ss,2); ss+=__shfl_xor(ss,4);
;       const float rn=rsqrtf(ss*(1.0f/128.0f)+1e-6f)*0.8f;
;       u32x4 w0,w1;
;       #pragma unroll
;       for(int q=0;q<4;++q){ w0[q]=cvtpk_s(d0[2*q]*rn,d0[2*q+1]*rn); w1[q]=cvtpk_s(d1[2*q]*rn,d1[2*q+1]*rn); }
;       *(u32x4*)(Mw+(long)row*OP+ch*8)=w0; *(u32x4*)(Mw+(long)row*OP+64+ch*8)=w1; }
.Lat_comb11:
	v_mov_b32_e32 v219, s7
	s_waitcnt vmcnt(0)
	v_fma_f32 v20, -v219, v148, v20
	v_fma_f32 v21, -v219, v149, v21
	v_fma_f32 v22, -v219, v150, v22
	v_fma_f32 v23, -v219, v151, v23
	v_fma_f32 v24, -v219, v152, v24
	v_fma_f32 v25, -v219, v153, v25
	v_fma_f32 v26, -v219, v154, v26
	v_fma_f32 v27, -v219, v155, v27
	v_fma_f32 v28, -v219, v156, v28
	v_fma_f32 v29, -v219, v157, v29
	v_fma_f32 v30, -v219, v158, v30
	v_fma_f32 v31, -v219, v159, v31
	v_fma_f32 v32, -v219, v160, v32
	v_fma_f32 v33, -v219, v161, v33
	v_fma_f32 v34, -v219, v162, v34
	v_fma_f32 v35, -v219, v163, v35
	v_fma_f32 v36, -v219, v164, v36
	v_fma_f32 v37, -v219, v165, v37
	v_fma_f32 v38, -v219, v166, v38
	v_fma_f32 v39, -v219, v167, v39
	v_fma_f32 v40, -v219, v168, v40
	v_fma_f32 v41, -v219, v169, v41
	v_fma_f32 v42, -v219, v170, v42
	v_fma_f32 v43, -v219, v171, v43
	v_fma_f32 v44, -v219, v172, v44
	v_fma_f32 v45, -v219, v173, v45
	v_fma_f32 v46, -v219, v174, v46
	v_fma_f32 v47, -v219, v175, v47
	v_fma_f32 v48, -v219, v176, v48
	v_fma_f32 v49, -v219, v177, v49
	v_fma_f32 v50, -v219, v178, v50
	v_fma_f32 v51, -v219, v179, v51
	v_fma_f32 v52, -v219, v180, v52
	v_fma_f32 v53, -v219, v181, v53
	v_fma_f32 v54, -v219, v182, v54
	v_fma_f32 v55, -v219, v183, v55
	v_fma_f32 v56, -v219, v184, v56
	v_fma_f32 v57, -v219, v185, v57
	v_fma_f32 v58, -v219, v186, v58
	v_fma_f32 v59, -v219, v187, v59
	v_fma_f32 v60, -v219, v188, v60
	v_fma_f32 v61, -v219, v189, v61
	v_fma_f32 v62, -v219, v190, v62
	v_fma_f32 v63, -v219, v191, v63
	v_fma_f32 v64, -v219, v192, v64
	v_fma_f32 v65, -v219, v193, v65
	v_fma_f32 v66, -v219, v194, v66
	v_fma_f32 v67, -v219, v195, v67
	v_fma_f32 v68, -v219, v196, v68
	v_fma_f32 v69, -v219, v197, v69
	v_fma_f32 v70, -v219, v198, v70
	v_fma_f32 v71, -v219, v199, v71
	v_fma_f32 v72, -v219, v200, v72
	v_fma_f32 v73, -v219, v201, v73
	v_fma_f32 v74, -v219, v202, v74
	v_fma_f32 v75, -v219, v203, v75
	v_fma_f32 v76, -v219, v204, v76
	v_fma_f32 v77, -v219, v205, v77
	v_fma_f32 v78, -v219, v206, v78
	v_fma_f32 v79, -v219, v207, v79
	v_fma_f32 v80, -v219, v208, v80
	v_fma_f32 v81, -v219, v209, v81
	v_fma_f32 v82, -v219, v210, v82
	v_fma_f32 v83, -v219, v211, v83
	s_mul_i32 s34, s5, 0x4200
	v_mul_u32_u24_e32 v221, 0x840, v2
	v_add_u32_e32 v221, v221, v240
	v_add_u32_e32 v221, s34, v221
	s_add_u32 s50, s66, 0x2e00400
	s_addc_u32 s51, s67, 0
	s_lshl_b32 s36, s9, 23
	s_add_u32 s50, s50, s36
	s_addc_u32 s51, s51, 0
	s_lshl_b32 s36, s13, 19
	s_add_u32 s50, s50, s36
	s_addc_u32 s51, s51, 0
	s_lshl_b32 s36, s10, 8
	s_add_u32 s50, s50, s36
	s_addc_u32 s51, s51, 0
	s_cmp_lg_u32 s6, 0
	s_cbranch_scc1 .Lat_skipst14
	ds_write_b32 v221, v20 offset:0
	ds_write_b32 v221, v21 offset:528
	ds_write_b32 v221, v22 offset:1056
	ds_write_b32 v221, v23 offset:1584
	ds_write_b32 v221, v24 offset:4224
	ds_write_b32 v221, v25 offset:4752
	ds_write_b32 v221, v26 offset:5280
	ds_write_b32 v221, v27 offset:5808
	ds_write_b32 v221, v28 offset:8448
	ds_write_b32 v221, v29 offset:8976
	ds_write_b32 v221, v30 offset:9504
	ds_write_b32 v221, v31 offset:10032
	ds_write_b32 v221, v32 offset:12672
	ds_write_b32 v221, v33 offset:13200
	ds_write_b32 v221, v34 offset:13728
	ds_write_b32 v221, v35 offset:14256
	ds_write_b32 v221, v36 offset:128
	ds_write_b32 v221, v37 offset:656
	ds_write_b32 v221, v38 offset:1184
	ds_write_b32 v221, v39 offset:1712
	ds_write_b32 v221, v40 offset:4352
	ds_write_b32 v221, v41 offset:4880
	ds_write_b32 v221, v42 offset:5408
	ds_write_b32 v221, v43 offset:5936
	ds_write_b32 v221, v44 offset:8576
	ds_write_b32 v221, v45 offset:9104
	ds_write_b32 v221, v46 offset:9632
	ds_write_b32 v221, v47 offset:10160
	ds_write_b32 v221, v48 offset:12800
	ds_write_b32 v221, v49 offset:13328
	ds_write_b32 v221, v50 offset:13856
	ds_write_b32 v221, v51 offset:14384
	ds_write_b32 v221, v52 offset:256
	ds_write_b32 v221, v53 offset:784
	ds_write_b32 v221, v54 offset:1312
	ds_write_b32 v221, v55 offset:1840
	ds_write_b32 v221, v56 offset:4480
	ds_write_b32 v221, v57 offset:5008
	ds_write_b32 v221, v58 offset:5536
	ds_write_b32 v221, v59 offset:6064
	ds_write_b32 v221, v60 offset:8704
	ds_write_b32 v221, v61 offset:9232
	ds_write_b32 v221, v62 offset:9760
	ds_write_b32 v221, v63 offset:10288
	ds_write_b32 v221, v64 offset:12928
	ds_write_b32 v221, v65 offset:13456
	ds_write_b32 v221, v66 offset:13984
	ds_write_b32 v221, v67 offset:14512
	ds_write_b32 v221, v68 offset:384
	ds_write_b32 v221, v69 offset:912
	ds_write_b32 v221, v70 offset:1440
	ds_write_b32 v221, v71 offset:1968
	ds_write_b32 v221, v72 offset:4608
	ds_write_b32 v221, v73 offset:5136
	ds_write_b32 v221, v74 offset:5664
	ds_write_b32 v221, v75 offset:6192
	ds_write_b32 v221, v76 offset:8832
	ds_write_b32 v221, v77 offset:9360
	ds_write_b32 v221, v78 offset:9888
	ds_write_b32 v221, v79 offset:10416
	ds_write_b32 v221, v80 offset:13056
	ds_write_b32 v221, v81 offset:13584
	ds_write_b32 v221, v82 offset:14112
	ds_write_b32 v221, v83 offset:14640
; __device__ __forceinline__ unsigned cvtpk_s(float lo,float hi){f32x2_t v={lo,hi};bf16x2_t b=__builtin_convertvector(v,bf16x2_t);return __builtin_bit_cast(unsigned,b);}
; template<int THRL,bool PART> __device__ __forceinline__ int attn_unit(const bf16*Qb,const bf16*__restrict__ Kh,const bf16*__restrict__ Vh,bf16*Ob,const int NT,const int vlim_in,char*shm,const int s0,const bool primed,const bf16*nKh,const bf16*nVh,bf16*fuseM,const float lam){
;     ...
;     for(int i=0;i<4;++i){const int row=i*8+(lane>>3),ch=lane&7; const u32x4 v=*(const u32x4*)(stg+row*64+ch*8);
;       const bf16*gp=Ow+(long)row*OP+ch*8; const u32x4 a=*(const u32x4*)(gp-192), c1=*(const u32x4*)(gp-128), b=*(const u32x4*)(gp-64);
;       float d0[8],d1[8],ss=0.f;
;       #pragma unroll
;       for(int q=0;q<4;++q){ d0[2*q]=__uint_as_float(a[q]<<16)-lam*__uint_as_float(b[q]<<16); d0[2*q+1]=__uint_as_float(a[q]&0xffff0000u)-lam*__uint_as_float(b[q]&0xffff0000u);
;         d1[2*q]=__uint_as_float(c1[q]<<16)-lam*__uint_as_float(v[q]<<16); d1[2*q+1]=__uint_as_float(c1[q]&0xffff0000u)-lam*__uint_as_float(v[q]&0xffff0000u);
;         ss+=d0[2*q]*d0[2*q]+d0[2*q+1]*d0[2*q+1]+d1[2*q]*d1[2*q]+d1[2*q+1]*d1[2*q+1]; }
;       ss+=__shfl_xor(ss,1); ss+=__shfl_xor(ss,2); ss+=__shfl_xor(ss,4);
;       const float rn=rsqrtf(ss*(1.0f/128.0f)+1e-6f)*0.8f;
;       u32x4 w0,w1;
;       #pragma unroll
;       for(int q=0;q<4;++q){ w0[q]=cvtpk_s(d0[2*q]*rn,d0[2*q+1]*rn); w1[q]=cvtpk_s(d1[2*q]*rn,d1[2*q+1]*rn); }
;       *(u32x4*)(Mw+(long)row*OP+ch*8)=w0; *(u32x4*)(Mw+(long)row*OP+64+ch*8)=w1; }
.Lat_skipst14:
	s_waitcnt lgkmcnt(0)
	s_barrier
	v_lshrrev_b32_e32 v223, 2, v252
	v_and_b32_e32 v224, 3, v252
	v_mul_u32_u24_e32 v222, 0x210, v223
	v_lshl_add_u32 v222, v224, 7, v222
	ds_read_b128 v[100:103], v222 offset:0
	ds_read_b128 v[104:107], v222 offset:16
	ds_read_b128 v[108:111], v222 offset:32
	ds_read_b128 v[112:115], v222 offset:48
	ds_read_b128 v[116:119], v222 offset:64
	ds_read_b128 v[120:123], v222 offset:80
	ds_read_b128 v[124:127], v222 offset:96
	ds_read_b128 v[128:131], v222 offset:112
	s_waitcnt lgkmcnt(0)
	v_mul_f32_e32 v219, v100, v100
	v_fmac_f32_e32 v219, v101, v101
	v_fmac_f32_e32 v219, v102, v102
	v_fmac_f32_e32 v219, v103, v103
	v_fmac_f32_e32 v219, v104, v104
	v_fmac_f32_e32 v219, v105, v105
	v_fmac_f32_e32 v219, v106, v106
	v_fmac_f32_e32 v219, v107, v107
	v_fmac_f32_e32 v219, v108, v108
	v_fmac_f32_e32 v219, v109, v109
	v_fmac_f32_e32 v219, v110, v110
	v_fmac_f32_e32 v219, v111, v111
	v_fmac_f32_e32 v219, v112, v112
	v_fmac_f32_e32 v219, v113, v113
	v_fmac_f32_e32 v219, v114, v114
	v_fmac_f32_e32 v219, v115, v115
	v_fmac_f32_e32 v219, v116, v116
	v_fmac_f32_e32 v219, v117, v117
	v_fmac_f32_e32 v219, v118, v118
	v_fmac_f32_e32 v219, v119, v119
	v_fmac_f32_e32 v219, v120, v120
	v_fmac_f32_e32 v219, v121, v121
	v_fmac_f32_e32 v219, v122, v122
	v_fmac_f32_e32 v219, v123, v123
	v_fmac_f32_e32 v219, v124, v124
	v_fmac_f32_e32 v219, v125, v125
	v_fmac_f32_e32 v219, v126, v126
	v_fmac_f32_e32 v219, v127, v127
	v_fmac_f32_e32 v219, v128, v128
	v_fmac_f32_e32 v219, v129, v129
	v_fmac_f32_e32 v219, v130, v130
	v_fmac_f32_e32 v219, v131, v131
	s_nop 1
	v_add_f32_dpp v219, v219, v219 quad_perm:[1,0,3,2] row_mask:0xf bank_mask:0xf
	s_nop 1
	v_add_f32_dpp v219, v219, v219 quad_perm:[2,3,0,1] row_mask:0xf bank_mask:0xf
	v_mov_b32_e32 v220, 0x358637bd
	v_fmamk_f32 v219, v219, 0x3c000000, v220
	v_rsq_f32_e32 v219, v219
	s_nop 0
	v_mul_f32_e32 v219, 0x3f4ccccd, v219
	v_mul_f32_e32 v100, v100, v219
	v_mul_f32_e32 v101, v101, v219
	v_mul_f32_e32 v102, v102, v219
	v_mul_f32_e32 v103, v103, v219
	v_mul_f32_e32 v104, v104, v219
	v_mul_f32_e32 v105, v105, v219
	v_mul_f32_e32 v106, v106, v219
	v_mul_f32_e32 v107, v107, v219
	v_mul_f32_e32 v108, v108, v219
	v_mul_f32_e32 v109, v109, v219
	v_mul_f32_e32 v110, v110, v219
	v_mul_f32_e32 v111, v111, v219
	v_mul_f32_e32 v112, v112, v219
	v_mul_f32_e32 v113, v113, v219
	v_mul_f32_e32 v114, v114, v219
	v_mul_f32_e32 v115, v115, v219
	v_mul_f32_e32 v116, v116, v219
	v_mul_f32_e32 v117, v117, v219
	v_mul_f32_e32 v118, v118, v219
	v_mul_f32_e32 v119, v119, v219
	v_mul_f32_e32 v120, v120, v219
	v_mul_f32_e32 v121, v121, v219
	v_mul_f32_e32 v122, v122, v219
	v_mul_f32_e32 v123, v123, v219
	v_mul_f32_e32 v124, v124, v219
	v_mul_f32_e32 v125, v125, v219
	v_mul_f32_e32 v126, v126, v219
	v_mul_f32_e32 v127, v127, v219
	v_mul_f32_e32 v128, v128, v219
	v_mul_f32_e32 v129, v129, v219
	v_mul_f32_e32 v130, v130, v219
	v_mul_f32_e32 v131, v131, v219
	v_cvt_pk_bf16_f32 v132, v100, v101
	v_cvt_pk_bf16_f32 v133, v102, v103
	v_cvt_pk_bf16_f32 v134, v104, v105
	v_cvt_pk_bf16_f32 v135, v106, v107
	v_cvt_pk_bf16_f32 v136, v108, v109
	v_cvt_pk_bf16_f32 v137, v110, v111
	v_cvt_pk_bf16_f32 v138, v112, v113
	v_cvt_pk_bf16_f32 v139, v114, v115
	v_cvt_pk_bf16_f32 v140, v116, v117
	v_cvt_pk_bf16_f32 v141, v118, v119
	v_cvt_pk_bf16_f32 v142, v120, v121
	v_cvt_pk_bf16_f32 v143, v122, v123
	v_cvt_pk_bf16_f32 v144, v124, v125
	v_cvt_pk_bf16_f32 v145, v126, v127
	v_cvt_pk_bf16_f32 v146, v128, v129
	v_cvt_pk_bf16_f32 v147, v130, v131
	v_lshlrev_b32_e32 v222, 11, v223
	v_lshl_add_u32 v222, v224, 6, v222
	global_store_dwordx4 v222, v[132:135], s[50:51]
	global_store_dwordx4 v222, v[136:139], s[50:51] offset:16
	global_store_dwordx4 v222, v[140:143], s[50:51] offset:32
	global_store_dwordx4 v222, v[144:147], s[50:51] offset:48
	s_barrier
	s_cmp_lg_u32 s6, 1
	s_cbranch_scc1 .Lat_skipst15
	ds_write_b32 v221, v20 offset:0
	ds_write_b32 v221, v21 offset:528
	ds_write_b32 v221, v22 offset:1056
	ds_write_b32 v221, v23 offset:1584
	ds_write_b32 v221, v24 offset:4224
	ds_write_b32 v221, v25 offset:4752
	ds_write_b32 v221, v26 offset:5280
	ds_write_b32 v221, v27 offset:5808
	ds_write_b32 v221, v28 offset:8448
	ds_write_b32 v221, v29 offset:8976
	ds_write_b32 v221, v30 offset:9504
	ds_write_b32 v221, v31 offset:10032
	ds_write_b32 v221, v32 offset:12672
	ds_write_b32 v221, v33 offset:13200
	ds_write_b32 v221, v34 offset:13728
	ds_write_b32 v221, v35 offset:14256
	ds_write_b32 v221, v36 offset:128
	ds_write_b32 v221, v37 offset:656
	ds_write_b32 v221, v38 offset:1184
	ds_write_b32 v221, v39 offset:1712
	ds_write_b32 v221, v40 offset:4352
	ds_write_b32 v221, v41 offset:4880
	ds_write_b32 v221, v42 offset:5408
	ds_write_b32 v221, v43 offset:5936
	ds_write_b32 v221, v44 offset:8576
	ds_write_b32 v221, v45 offset:9104
	ds_write_b32 v221, v46 offset:9632
	ds_write_b32 v221, v47 offset:10160
	ds_write_b32 v221, v48 offset:12800
	ds_write_b32 v221, v49 offset:13328
	ds_write_b32 v221, v50 offset:13856
	ds_write_b32 v221, v51 offset:14384
	ds_write_b32 v221, v52 offset:256
	ds_write_b32 v221, v53 offset:784
	ds_write_b32 v221, v54 offset:1312
	ds_write_b32 v221, v55 offset:1840
	ds_write_b32 v221, v56 offset:4480
	ds_write_b32 v221, v57 offset:5008
	ds_write_b32 v221, v58 offset:5536
	ds_write_b32 v221, v59 offset:6064
	ds_write_b32 v221, v60 offset:8704
	ds_write_b32 v221, v61 offset:9232
	ds_write_b32 v221, v62 offset:9760
	ds_write_b32 v221, v63 offset:10288
	ds_write_b32 v221, v64 offset:12928
	ds_write_b32 v221, v65 offset:13456
	ds_write_b32 v221, v66 offset:13984
	ds_write_b32 v221, v67 offset:14512
	ds_write_b32 v221, v68 offset:384
	ds_write_b32 v221, v69 offset:912
	ds_write_b32 v221, v70 offset:1440
	ds_write_b32 v221, v71 offset:1968
	ds_write_b32 v221, v72 offset:4608
	ds_write_b32 v221, v73 offset:5136
	ds_write_b32 v221, v74 offset:5664
	ds_write_b32 v221, v75 offset:6192
	ds_write_b32 v221, v76 offset:8832
	ds_write_b32 v221, v77 offset:9360
	ds_write_b32 v221, v78 offset:9888
	ds_write_b32 v221, v79 offset:10416
	ds_write_b32 v221, v80 offset:13056
	ds_write_b32 v221, v81 offset:13584
	ds_write_b32 v221, v82 offset:14112
	ds_write_b32 v221, v83 offset:14640
; template<int THRL,bool PART> __device__ __forceinline__ int attn_unit(const bf16*Qb,const bf16*__restrict__ Kh,const bf16*__restrict__ Vh,bf16*Ob,const int NT,const int vlim_in,char*shm,const int s0,const bool primed,const bf16*nKh,const bf16*nVh,bf16*fuseM,const float lam){
;     ...
;     for(int i=0;i<4;++i){const int row=i*8+(lane>>3),ch=lane&7; const u32x4 v=*(const u32x4*)(stg+row*64+ch*8);
;       const bf16*gp=Ow+(long)row*OP+ch*8; const u32x4 a=*(const u32x4*)(gp-192), c1=*(const u32x4*)(gp-128), b=*(const u32x4*)(gp-64);
;       float d0[8],d1[8],ss=0.f;
;       #pragma unroll
;       for(int q=0;q<4;++q){ d0[2*q]=__uint_as_float(a[q]<<16)-lam*__uint_as_float(b[q]<<16); d0[2*q+1]=__uint_as_float(a[q]&0xffff0000u)-lam*__uint_as_float(b[q]&0xffff0000u);
;         d1[2*q]=__uint_as_float(c1[q]<<16)-lam*__uint_as_float(v[q]<<16); d1[2*q+1]=__uint_as_float(c1[q]&0xffff0000u)-lam*__uint_as_float(v[q]&0xffff0000u);
;         ss+=d0[2*q]*d0[2*q]+d0[2*q+1]*d0[2*q+1]+d1[2*q]*d1[2*q]+d1[2*q+1]*d1[2*q+1]; }
;       ss+=__shfl_xor(ss,1); ss+=__shfl_xor(ss,2); ss+=__shfl_xor(ss,4);
;       const float rn=rsqrtf(ss*(1.0f/128.0f)+1e-6f)*0.8f;
;       u32x4 w0,w1;
;       #pragma unroll
;       for(int q=0;q<4;++q){ w0[q]=cvtpk_s(d0[2*q]*rn,d0[2*q+1]*rn); w1[q]=cvtpk_s(d1[2*q]*rn,d1[2*q+1]*rn); }
;       *(u32x4*)(Mw+(long)row*OP+ch*8)=w0; *(u32x4*)(Mw+(long)row*OP+64+ch*8)=w1; }
; __global__ void __launch_bounds__(NWAVES * 64, 2) mk_fwd(Args args) {
;     ...
;             for (int i = 0; i < 8; ++i) { const int qb = (i >> 2) ? 15 - s : s, j = (i >> 1) & 1, vh = i & 1;
;                 const bf16* Qp = Qb + (size_t)(b * 4096 + qb * 256) * 512 + (hd * 2 + j) * 64; const bf16* Kp = Kb + (size_t)(b * 4096) * 512 + (hd * 2 + j) * 64; const bf16* Vp = Vb + (size_t)(b * 4096) * 512 + (hd * 2 + vh) * 64;
;                 bf16* Op = ATTO + (size_t)(b * 4096 + qb * 256) * 1024 + ((hd * 2 + j) * 2 + vh) * 64;
;                 bf16* Mp = ((i & 3) == 3) ? H + (size_t)(b * 4096 + qb * 256) * 1024 + 512 + hd * 128 : nullptr;
;                 const bool more = i < 7; const int jn = ((i + 1) >> 1) & 1, vn = (i + 1) & 1;
;                 const bf16* nK = Kb + (size_t)(b * 4096) * 512 + (hd * 2 + jn) * 64; const bf16* nV = Vb + (size_t)(b * 4096) * 512 + (hd * 2 + vn) * 64;
.Lat_skipst15:
	s_waitcnt lgkmcnt(0)
	s_barrier
	v_lshrrev_b32_e32 v223, 2, v252
	v_and_b32_e32 v224, 3, v252
	v_mul_u32_u24_e32 v222, 0x210, v223
	v_lshl_add_u32 v222, v224, 7, v222
	ds_read_b128 v[100:103], v222 offset:0
	ds_read_b128 v[104:107], v222 offset:16
	ds_read_b128 v[108:111], v222 offset:32
	ds_read_b128 v[112:115], v222 offset:48
	ds_read_b128 v[116:119], v222 offset:64
	ds_read_b128 v[120:123], v222 offset:80
	ds_read_b128 v[124:127], v222 offset:96
	ds_read_b128 v[128:131], v222 offset:112
	s_waitcnt lgkmcnt(0)
	v_mul_f32_e32 v219, v100, v100
	v_fmac_f32_e32 v219, v101, v101
	v_fmac_f32_e32 v219, v102, v102
	v_fmac_f32_e32 v219, v103, v103
	v_fmac_f32_e32 v219, v104, v104
	v_fmac_f32_e32 v219, v105, v105
	v_fmac_f32_e32 v219, v106, v106
	v_fmac_f32_e32 v219, v107, v107
	v_fmac_f32_e32 v219, v108, v108
	v_fmac_f32_e32 v219, v109, v109
	v_fmac_f32_e32 v219, v110, v110
	v_fmac_f32_e32 v219, v111, v111
	v_fmac_f32_e32 v219, v112, v112
	v_fmac_f32_e32 v219, v113, v113
	v_fmac_f32_e32 v219, v114, v114
	v_fmac_f32_e32 v219, v115, v115
	v_fmac_f32_e32 v219, v116, v116
	v_fmac_f32_e32 v219, v117, v117
	v_fmac_f32_e32 v219, v118, v118
	v_fmac_f32_e32 v219, v119, v119
	v_fmac_f32_e32 v219, v120, v120
	v_fmac_f32_e32 v219, v121, v121
	v_fmac_f32_e32 v219, v122, v122
	v_fmac_f32_e32 v219, v123, v123
	v_fmac_f32_e32 v219, v124, v124
	v_fmac_f32_e32 v219, v125, v125
	v_fmac_f32_e32 v219, v126, v126
	v_fmac_f32_e32 v219, v127, v127
	v_fmac_f32_e32 v219, v128, v128
	v_fmac_f32_e32 v219, v129, v129
	v_fmac_f32_e32 v219, v130, v130
	v_fmac_f32_e32 v219, v131, v131
	s_nop 1
	v_add_f32_dpp v219, v219, v219 quad_perm:[1,0,3,2] row_mask:0xf bank_mask:0xf
	s_nop 1
	v_add_f32_dpp v219, v219, v219 quad_perm:[2,3,0,1] row_mask:0xf bank_mask:0xf
	v_mov_b32_e32 v220, 0x358637bd
	v_fmamk_f32 v219, v219, 0x3c000000, v220
	v_rsq_f32_e32 v219, v219
	s_nop 0
	v_mul_f32_e32 v219, 0x3f4ccccd, v219
	v_mul_f32_e32 v100, v100, v219
	v_mul_f32_e32 v101, v101, v219
	v_mul_f32_e32 v102, v102, v219
	v_mul_f32_e32 v103, v103, v219
	v_mul_f32_e32 v104, v104, v219
	v_mul_f32_e32 v105, v105, v219
	v_mul_f32_e32 v106, v106, v219
	v_mul_f32_e32 v107, v107, v219
	v_mul_f32_e32 v108, v108, v219
	v_mul_f32_e32 v109, v109, v219
	v_mul_f32_e32 v110, v110, v219
	v_mul_f32_e32 v111, v111, v219
	v_mul_f32_e32 v112, v112, v219
	v_mul_f32_e32 v113, v113, v219
	v_mul_f32_e32 v114, v114, v219
	v_mul_f32_e32 v115, v115, v219
	v_mul_f32_e32 v116, v116, v219
	v_mul_f32_e32 v117, v117, v219
	v_mul_f32_e32 v118, v118, v219
	v_mul_f32_e32 v119, v119, v219
	v_mul_f32_e32 v120, v120, v219
	v_mul_f32_e32 v121, v121, v219
	v_mul_f32_e32 v122, v122, v219
	v_mul_f32_e32 v123, v123, v219
	v_mul_f32_e32 v124, v124, v219
	v_mul_f32_e32 v125, v125, v219
	v_mul_f32_e32 v126, v126, v219
	v_mul_f32_e32 v127, v127, v219
	v_mul_f32_e32 v128, v128, v219
	v_mul_f32_e32 v129, v129, v219
	v_mul_f32_e32 v130, v130, v219
	v_mul_f32_e32 v131, v131, v219
	v_cvt_pk_bf16_f32 v132, v100, v101
	v_cvt_pk_bf16_f32 v133, v102, v103
	v_cvt_pk_bf16_f32 v134, v104, v105
	v_cvt_pk_bf16_f32 v135, v106, v107
	v_cvt_pk_bf16_f32 v136, v108, v109
	v_cvt_pk_bf16_f32 v137, v110, v111
	v_cvt_pk_bf16_f32 v138, v112, v113
	v_cvt_pk_bf16_f32 v139, v114, v115
	v_cvt_pk_bf16_f32 v140, v116, v117
	v_cvt_pk_bf16_f32 v141, v118, v119
	v_cvt_pk_bf16_f32 v142, v120, v121
	v_cvt_pk_bf16_f32 v143, v122, v123
	v_cvt_pk_bf16_f32 v144, v124, v125
	v_cvt_pk_bf16_f32 v145, v126, v127
	v_cvt_pk_bf16_f32 v146, v128, v129
	v_cvt_pk_bf16_f32 v147, v130, v131
	v_lshlrev_b32_e32 v222, 11, v223
	v_lshl_add_u32 v222, v224, 6, v222
	v_add_u32_e32 v222, 0x40000, v222
	global_store_dwordx4 v222, v[132:135], s[50:51]
	global_store_dwordx4 v222, v[136:139], s[50:51] offset:16
	global_store_dwordx4 v222, v[140:143], s[50:51] offset:32
	global_store_dwordx4 v222, v[144:147], s[50:51] offset:48
.Lat_udone12:
	s_barrier
	s_add_i32 s14, s14, 1
	s_cmp_lt_u32 s14, 2
	s_cbranch_scc1 .Lat_j
	s_add_i32 s12, s12, 1
	s_cmp_lt_u32 s12, 2
	s_cbranch_scc1 .Lat_blk
	s_add_i32 s8, s8, s69
	s_cmpk_gt_i32 s8, 0xff
	s_cbranch_scc0 .Lat_v
	s_branch .LBB0_1021
